# MLP1 epilogue: row statistics loaded once per lane (2 rows) at the top and shared with ds_bpermute instead of 8 serial per-row-group load+reduce rounds
# speedup vs baseline: 1.0651x; 1.0044x over previous
.LBB0_141:
	s_lshl_b32 s1, s2, 8
	s_lshl_b32 s0, s0, 8
	v_mov_b32_e32 v64, v208
	v_mov_b32_e32 v160, v179
	s_add_i32 s1, s1, s78
	s_or_b32 s0, s0, s79
	s_nop 0
	v_lshl_add_u32 v196, v64, 3, s0
	v_add_u32_e32 v198, s1, v160
	v_ashrrev_i32_e32 v197, 31, v196
	v_ashrrev_i32_e32 v199, 31, v198
	v_lshlrev_b64 v[64:65], 2, v[196:197]
	v_lshl_add_u64 v[66:67], s[54:55], 0, v[64:65]
	v_lshl_add_u64 v[64:65], s[58:59], 0, v[64:65]
	global_load_dwordx4 v[100:103], v[66:67], off offset:16
	global_load_dwordx4 v[92:95], v[66:67], off
	global_load_dwordx4 v[96:99], v[64:65], off offset:16
	global_load_dwordx4 v[88:91], v[64:65], off
	global_load_dwordx4 v[76:79], v[66:67], off offset:528
	global_load_dwordx4 v[68:71], v[66:67], off offset:512
	global_load_dwordx4 v[72:75], v[64:65], off offset:528
	s_nop 0
	global_load_dwordx4 v[64:67], v[64:65], off offset:512
	s_nop 0
	v_lshl_add_u32 v170, v208, 4, v198
	v_lshlrev_b32_e32 v170, 5, v170
	v_add_u32_e32 v232, 0x1000, v170
	global_load_dwordx4 v[160:163], v170, s[56:57] offset:16
	global_load_dwordx4 v[164:167], v170, s[56:57]
	global_load_dwordx4 v[212:215], v232, s[56:57] offset:16
	global_load_dwordx4 v[216:219], v232, s[56:57]
	v_lshlrev_b32_e32 v211, 2, v179
	s_mov_b32 s0, 0x3a800000
	s_mov_b32 s1, 0x800000
	v_add_u32_e32 v200, 16, v198
	v_ashrrev_i32_e32 v201, 31, v200
	v_lshlrev_b64 v[206:207], 13, v[198:199]
	v_lshl_add_u64 v[206:207], s[24:25], 0, v[206:207]
	v_lshl_add_u64 v[206:207], v[196:197], 1, v[206:207]
	s_waitcnt vmcnt(0)
	v_pk_add_f32 v[160:161], v[160:161], v[162:163]
	v_pk_add_f32 v[164:165], v[164:165], v[166:167]
	v_pk_add_f32 v[160:161], v[164:165], v[160:161]
	v_pk_mul_f32 v[160:161], v[160:161], s[0:1] op_sel_hi:[1,0]
	v_fma_f32 v164, -v160, v160, v161
	v_max_f32_e32 v164, 0, v164
	v_add_f32_e32 v164, 0x3727c5ac, v164
	v_cmp_gt_f32_e32 vcc, s1, v164
	v_mul_f32_e32 v165, 0x4b800000, v164
	v_mov_b32_e32 v220, v160
	v_cndmask_b32_e32 v164, v164, v165, vcc
	v_rsq_f32_e32 v164, v164
	s_nop 0
	v_mul_f32_e32 v165, 0x45800000, v164
	v_cndmask_b32_e32 v221, v164, v165, vcc
	v_pk_add_f32 v[212:213], v[212:213], v[214:215]
	v_pk_add_f32 v[216:217], v[216:217], v[218:219]
	v_pk_add_f32 v[212:213], v[216:217], v[212:213]
	v_pk_mul_f32 v[212:213], v[212:213], s[0:1] op_sel_hi:[1,0]
	v_fma_f32 v216, -v212, v212, v213
	v_max_f32_e32 v216, 0, v216
	v_add_f32_e32 v216, 0x3727c5ac, v216
	v_cmp_gt_f32_e32 vcc, s1, v216
	v_mul_f32_e32 v217, 0x4b800000, v216
	v_mov_b32_e32 v222, v212
	v_cndmask_b32_e32 v216, v216, v217, vcc
	v_rsq_f32_e32 v216, v216
	s_nop 0
	v_mul_f32_e32 v217, 0x45800000, v216
	v_cndmask_b32_e32 v223, v216, v217, vcc
	ds_bpermute_b32 v174, v211, v220
	ds_bpermute_b32 v175, v211, v221
	ds_bpermute_b32 v176, v211, v220 offset:64
	ds_bpermute_b32 v177, v211, v221 offset:64
	v_xor_b32_e32 v103, 0x80000000, v103
	v_xor_b32_e32 v102, 0x80000000, v102
	v_xor_b32_e32 v95, 0x80000000, v95
	v_xor_b32_e32 v94, 0x80000000, v94
	s_waitcnt lgkmcnt(2)
	v_mov_b32_e32 v202, v174
	v_mov_b32_e32 v204, v175
	v_mov_b32_e32 v203, v202
	v_mov_b32_e32 v205, v204
	v_cmp_gt_i32_e32 vcc, 2.0, v196
	s_and_saveexec_b64 s[0:1], vcc
	s_cbranch_execz .LBB0_143
	v_pk_fma_f32 v[152:153], v[92:93], v[202:203], v[152:153] neg_lo:[1,0,0] neg_hi:[1,0,0]
	v_pk_fma_f32 v[152:153], v[152:153], v[204:205], v[88:89]
	v_max_f32_e32 v152, 0, v152
	v_max_f32_e32 v153, 0, v153
	v_pk_mul_f32 v[152:153], v[152:153], v[152:153]
	v_pk_fma_f32 v[154:155], v[94:95], v[202:203], v[154:155]
	v_pk_fma_f32 v[154:155], v[154:155], v[204:205], v[90:91]
	v_max_f32_e32 v154, 0, v154
	v_max_f32_e32 v155, 0, v155
	v_pk_fma_f32 v[156:157], v[100:101], v[202:203], v[156:157] neg_lo:[1,0,0] neg_hi:[1,0,0]
	v_pk_mul_f32 v[154:155], v[154:155], v[154:155]
	v_pk_fma_f32 v[156:157], v[156:157], v[204:205], v[96:97]
	v_cvt_pk_bf16_f32 v152, v152, v153
	v_cvt_pk_bf16_f32 v153, v154, v155
	v_pk_fma_f32 v[158:159], v[102:103], v[202:203], v[158:159]
	v_max_f32_e32 v156, 0, v156
	v_max_f32_e32 v157, 0, v157
	v_pk_fma_f32 v[158:159], v[158:159], v[204:205], v[98:99]
	v_pk_mul_f32 v[156:157], v[156:157], v[156:157]
	v_max_f32_e32 v158, 0, v158
	v_max_f32_e32 v159, 0, v159
	v_pk_mul_f32 v[158:159], v[158:159], v[158:159]
	v_cvt_pk_bf16_f32 v154, v156, v157
	v_cvt_pk_bf16_f32 v155, v158, v159
	global_store_dwordx4 v[206:207], v[152:155], off

.LBB0_145:
	s_or_b64 exec, exec, s[0:1]
	s_waitcnt lgkmcnt(0)
	v_mov_b32_e32 v154, v176
	v_mov_b32_e32 v156, v177
	ds_bpermute_b32 v174, v211, v220 offset:128
	ds_bpermute_b32 v175, v211, v221 offset:128
	v_lshlrev_b64 v[158:159], 13, v[200:201]
	v_lshl_add_u64 v[158:159], s[24:25], 0, v[158:159]
	v_lshl_add_u64 v[158:159], v[196:197], 1, v[158:159]
	v_mov_b32_e32 v155, v154
	v_add_u32_e32 v78, 32, v198
	v_ashrrev_i32_e32 v79, 31, v78
	v_mov_b32_e32 v157, v156
	s_and_saveexec_b64 s[0:1], vcc
	s_cbranch_execz .LBB0_147
	v_pk_fma_f32 v[136:137], v[92:93], v[154:155], v[136:137] neg_lo:[1,0,0] neg_hi:[1,0,0]
	v_pk_fma_f32 v[136:137], v[136:137], v[156:157], v[88:89]
	v_max_f32_e32 v136, 0, v136
	v_max_f32_e32 v137, 0, v137
	v_pk_mul_f32 v[136:137], v[136:137], v[136:137]
	v_pk_fma_f32 v[142:143], v[102:103], v[154:155], v[142:143]
	v_pk_fma_f32 v[138:139], v[94:95], v[154:155], v[138:139]
	v_pk_fma_f32 v[138:139], v[138:139], v[156:157], v[90:91]
	v_max_f32_e32 v138, 0, v138
	v_max_f32_e32 v139, 0, v139
	v_pk_fma_f32 v[140:141], v[100:101], v[154:155], v[140:141] neg_lo:[1,0,0] neg_hi:[1,0,0]
	v_pk_mul_f32 v[138:139], v[138:139], v[138:139]
	v_pk_fma_f32 v[140:141], v[140:141], v[156:157], v[96:97]
	v_cvt_pk_bf16_f32 v136, v136, v137
	v_cvt_pk_bf16_f32 v137, v138, v139
	v_max_f32_e32 v140, 0, v140
	v_max_f32_e32 v141, 0, v141
	v_pk_fma_f32 v[142:143], v[142:143], v[156:157], v[98:99]
	v_pk_mul_f32 v[140:141], v[140:141], v[140:141]
	v_max_f32_e32 v142, 0, v142
	v_max_f32_e32 v143, 0, v143
	v_pk_mul_f32 v[142:143], v[142:143], v[142:143]
	v_cvt_pk_bf16_f32 v138, v140, v141
	v_cvt_pk_bf16_f32 v139, v142, v143
	global_store_dwordx4 v[158:159], v[136:139], off

.LBB0_149:
	s_or_b64 exec, exec, s[0:1]
	s_waitcnt lgkmcnt(0)
	v_mov_b32_e32 v138, v174
	v_mov_b32_e32 v140, v175
	ds_bpermute_b32 v176, v211, v220 offset:192
	ds_bpermute_b32 v177, v211, v221 offset:192
	v_add_u32_e32 v136, 48, v198
	v_ashrrev_i32_e32 v137, 31, v136
	v_lshlrev_b64 v[78:79], 13, v[78:79]
	v_lshl_add_u64 v[78:79], s[24:25], 0, v[78:79]
	v_lshl_add_u64 v[78:79], v[196:197], 1, v[78:79]
	v_mov_b32_e32 v139, v138
	v_mov_b32_e32 v141, v140
	s_and_saveexec_b64 s[0:1], vcc
	s_cbranch_execz .LBB0_151
	v_pk_fma_f32 v[120:121], v[92:93], v[138:139], v[120:121] neg_lo:[1,0,0] neg_hi:[1,0,0]
	v_pk_fma_f32 v[120:121], v[120:121], v[140:141], v[88:89]
	v_max_f32_e32 v120, 0, v120
	v_max_f32_e32 v121, 0, v121
	v_pk_mul_f32 v[120:121], v[120:121], v[120:121]
	v_pk_fma_f32 v[126:127], v[102:103], v[138:139], v[126:127]
	v_pk_fma_f32 v[122:123], v[94:95], v[138:139], v[122:123]
	v_pk_fma_f32 v[122:123], v[122:123], v[140:141], v[90:91]
	v_max_f32_e32 v122, 0, v122
	v_max_f32_e32 v123, 0, v123
	v_pk_fma_f32 v[124:125], v[100:101], v[138:139], v[124:125] neg_lo:[1,0,0] neg_hi:[1,0,0]
	v_pk_mul_f32 v[122:123], v[122:123], v[122:123]
	v_pk_fma_f32 v[124:125], v[124:125], v[140:141], v[96:97]
	v_cvt_pk_bf16_f32 v120, v120, v121
	v_cvt_pk_bf16_f32 v121, v122, v123
	v_max_f32_e32 v124, 0, v124
	v_max_f32_e32 v125, 0, v125
	v_pk_fma_f32 v[126:127], v[126:127], v[140:141], v[98:99]
	v_pk_mul_f32 v[124:125], v[124:125], v[124:125]
	v_max_f32_e32 v126, 0, v126
	v_max_f32_e32 v127, 0, v127
	v_pk_mul_f32 v[126:127], v[126:127], v[126:127]
	v_cvt_pk_bf16_f32 v122, v124, v125
	v_cvt_pk_bf16_f32 v123, v126, v127
	global_store_dwordx4 v[78:79], v[120:123], off

.LBB0_153:
	s_or_b64 exec, exec, s[0:1]
	s_waitcnt lgkmcnt(0)
	v_mov_b32_e32 v78, v176
	v_mov_b32_e32 v122, v177
	ds_bpermute_b32 v174, v211, v222
	ds_bpermute_b32 v175, v211, v223
	v_add_u32_e32 v120, 0x80, v198
	v_ashrrev_i32_e32 v121, 31, v120
	v_lshlrev_b64 v[124:125], 13, v[136:137]
	v_lshl_add_u64 v[124:125], s[24:25], 0, v[124:125]
	v_lshl_add_u64 v[124:125], v[196:197], 1, v[124:125]
	v_mov_b32_e32 v79, v78
	v_mov_b32_e32 v123, v122
	s_and_saveexec_b64 s[0:1], vcc
	s_cbranch_execz .LBB0_155
	v_pk_fma_f32 v[104:105], v[92:93], v[78:79], v[104:105] neg_lo:[1,0,0] neg_hi:[1,0,0]
	v_pk_fma_f32 v[104:105], v[104:105], v[122:123], v[88:89]
	v_max_f32_e32 v104, 0, v104
	v_max_f32_e32 v105, 0, v105
	v_pk_mul_f32 v[104:105], v[104:105], v[104:105]
	v_pk_fma_f32 v[110:111], v[102:103], v[78:79], v[110:111]
	v_pk_fma_f32 v[106:107], v[94:95], v[78:79], v[106:107]
	v_pk_fma_f32 v[106:107], v[106:107], v[122:123], v[90:91]
	v_max_f32_e32 v106, 0, v106
	v_max_f32_e32 v107, 0, v107
	v_pk_fma_f32 v[108:109], v[100:101], v[78:79], v[108:109] neg_lo:[1,0,0] neg_hi:[1,0,0]
	v_pk_mul_f32 v[106:107], v[106:107], v[106:107]
	v_pk_fma_f32 v[108:109], v[108:109], v[122:123], v[96:97]
	v_cvt_pk_bf16_f32 v104, v104, v105
	v_cvt_pk_bf16_f32 v105, v106, v107
	v_max_f32_e32 v108, 0, v108
	v_max_f32_e32 v109, 0, v109
	v_pk_fma_f32 v[110:111], v[110:111], v[122:123], v[98:99]
	v_pk_mul_f32 v[108:109], v[108:109], v[108:109]
	v_max_f32_e32 v110, 0, v110
	v_max_f32_e32 v111, 0, v111
	v_pk_mul_f32 v[110:111], v[110:111], v[110:111]
	v_cvt_pk_bf16_f32 v106, v108, v109
	v_cvt_pk_bf16_f32 v107, v110, v111
	global_store_dwordx4 v[124:125], v[104:107], off

.LBB0_157:
	s_or_b64 exec, exec, s[0:1]
	s_waitcnt lgkmcnt(0)
	v_mov_b32_e32 v104, v174
	v_mov_b32_e32 v106, v175
	ds_bpermute_b32 v176, v211, v222 offset:64
	ds_bpermute_b32 v177, v211, v223 offset:64
	v_add_u32_e32 v86, 0x90, v198
	v_ashrrev_i32_e32 v87, 31, v86
	v_lshlrev_b64 v[108:109], 13, v[120:121]
	v_lshl_add_u64 v[108:109], s[24:25], 0, v[108:109]
	v_lshl_add_u64 v[108:109], v[196:197], 1, v[108:109]
	v_mov_b32_e32 v105, v104
	v_mov_b32_e32 v107, v106
	s_and_saveexec_b64 s[0:1], vcc
	s_cbranch_execz .LBB0_159
	v_pk_fma_f32 v[56:57], v[92:93], v[104:105], v[56:57] neg_lo:[1,0,0] neg_hi:[1,0,0]
	v_pk_fma_f32 v[56:57], v[56:57], v[106:107], v[88:89]
	v_max_f32_e32 v56, 0, v56
	v_max_f32_e32 v57, 0, v57
	v_pk_mul_f32 v[56:57], v[56:57], v[56:57]
	v_pk_fma_f32 v[62:63], v[102:103], v[104:105], v[62:63]
	v_pk_fma_f32 v[58:59], v[94:95], v[104:105], v[58:59]
	v_pk_fma_f32 v[58:59], v[58:59], v[106:107], v[90:91]
	v_max_f32_e32 v58, 0, v58
	v_max_f32_e32 v59, 0, v59
	v_pk_fma_f32 v[60:61], v[100:101], v[104:105], v[60:61] neg_lo:[1,0,0] neg_hi:[1,0,0]
	v_pk_mul_f32 v[58:59], v[58:59], v[58:59]
	v_pk_fma_f32 v[60:61], v[60:61], v[106:107], v[96:97]
	v_cvt_pk_bf16_f32 v56, v56, v57
	v_cvt_pk_bf16_f32 v57, v58, v59
	v_max_f32_e32 v60, 0, v60
	v_max_f32_e32 v61, 0, v61
	v_pk_fma_f32 v[62:63], v[62:63], v[106:107], v[98:99]
	v_pk_mul_f32 v[60:61], v[60:61], v[60:61]
	v_max_f32_e32 v62, 0, v62
	v_max_f32_e32 v63, 0, v63
	v_pk_mul_f32 v[62:63], v[62:63], v[62:63]
	v_cvt_pk_bf16_f32 v58, v60, v61
	v_cvt_pk_bf16_f32 v59, v62, v63
	global_store_dwordx4 v[108:109], v[56:59], off

.LBB0_161:
	s_or_b64 exec, exec, s[0:1]
	s_waitcnt lgkmcnt(0)
	v_mov_b32_e32 v58, v176
	v_mov_b32_e32 v60, v177
	ds_bpermute_b32 v174, v211, v222 offset:128
	ds_bpermute_b32 v175, v211, v223 offset:128
	v_add_u32_e32 v56, 0xa0, v198
	v_ashrrev_i32_e32 v57, 31, v56
	v_lshlrev_b64 v[62:63], 13, v[86:87]
	v_lshl_add_u64 v[62:63], s[24:25], 0, v[62:63]
	v_lshl_add_u64 v[62:63], v[196:197], 1, v[62:63]
	v_mov_b32_e32 v59, v58
	v_mov_b32_e32 v61, v60
	s_and_saveexec_b64 s[0:1], vcc
	s_cbranch_execz .LBB0_163
	v_pk_fma_f32 v[40:41], v[92:93], v[58:59], v[40:41] neg_lo:[1,0,0] neg_hi:[1,0,0]
	v_pk_fma_f32 v[40:41], v[40:41], v[60:61], v[88:89]
	v_max_f32_e32 v40, 0, v40
	v_max_f32_e32 v41, 0, v41
	v_pk_mul_f32 v[40:41], v[40:41], v[40:41]
	v_pk_fma_f32 v[46:47], v[102:103], v[58:59], v[46:47]
	v_pk_fma_f32 v[42:43], v[94:95], v[58:59], v[42:43]
	v_pk_fma_f32 v[42:43], v[42:43], v[60:61], v[90:91]
	v_max_f32_e32 v42, 0, v42
	v_max_f32_e32 v43, 0, v43
	v_pk_fma_f32 v[44:45], v[100:101], v[58:59], v[44:45] neg_lo:[1,0,0] neg_hi:[1,0,0]
	v_pk_mul_f32 v[42:43], v[42:43], v[42:43]
	v_pk_fma_f32 v[44:45], v[44:45], v[60:61], v[96:97]
	v_cvt_pk_bf16_f32 v40, v40, v41
	v_cvt_pk_bf16_f32 v41, v42, v43
	v_max_f32_e32 v44, 0, v44
	v_max_f32_e32 v45, 0, v45
	v_pk_fma_f32 v[46:47], v[46:47], v[60:61], v[98:99]
	v_pk_mul_f32 v[44:45], v[44:45], v[44:45]
	v_max_f32_e32 v46, 0, v46
	v_max_f32_e32 v47, 0, v47
	v_pk_mul_f32 v[46:47], v[46:47], v[46:47]
	v_cvt_pk_bf16_f32 v42, v44, v45
	v_cvt_pk_bf16_f32 v43, v46, v47
	global_store_dwordx4 v[62:63], v[40:43], off

.LBB0_165:
	s_or_b64 exec, exec, s[0:1]
	s_waitcnt lgkmcnt(0)
	v_mov_b32_e32 v42, v174
	v_mov_b32_e32 v44, v175
	ds_bpermute_b32 v176, v211, v222 offset:192
	ds_bpermute_b32 v177, v211, v223 offset:192
	v_add_u32_e32 v40, 0xb0, v198
	v_ashrrev_i32_e32 v41, 31, v40
	v_lshlrev_b64 v[46:47], 13, v[56:57]
	v_lshl_add_u64 v[46:47], s[24:25], 0, v[46:47]
	v_lshl_add_u64 v[46:47], v[196:197], 1, v[46:47]
	v_mov_b32_e32 v43, v42
	v_mov_b32_e32 v45, v44
	s_and_saveexec_b64 s[0:1], vcc
	s_cbranch_execz .LBB0_167
	v_pk_fma_f32 v[24:25], v[92:93], v[42:43], v[24:25] neg_lo:[1,0,0] neg_hi:[1,0,0]
	v_mov_b32_e32 v48, v42
	v_pk_fma_f32 v[24:25], v[24:25], v[44:45], v[88:89]
	v_mov_b32_e32 v49, v42
	v_max_f32_e32 v24, 0, v24
	v_max_f32_e32 v25, 0, v25
	v_pk_mul_f32 v[24:25], v[24:25], v[24:25]
	v_pk_fma_f32 v[30:31], v[102:103], v[42:43], v[30:31]
	v_mov_b32_e32 v50, v44
	v_mov_b32_e32 v51, v44
	v_pk_fma_f32 v[26:27], v[94:95], v[42:43], v[26:27]
	v_pk_fma_f32 v[26:27], v[26:27], v[44:45], v[90:91]
	v_max_f32_e32 v26, 0, v26
	v_max_f32_e32 v27, 0, v27
	v_pk_fma_f32 v[28:29], v[100:101], v[42:43], v[28:29] neg_lo:[1,0,0] neg_hi:[1,0,0]
	v_pk_mul_f32 v[26:27], v[26:27], v[26:27]
	v_pk_fma_f32 v[28:29], v[28:29], v[44:45], v[96:97]
	v_cvt_pk_bf16_f32 v24, v24, v25
	v_cvt_pk_bf16_f32 v25, v26, v27
	v_max_f32_e32 v28, 0, v28
	v_max_f32_e32 v29, 0, v29
	v_pk_fma_f32 v[30:31], v[30:31], v[44:45], v[98:99]
	v_pk_mul_f32 v[28:29], v[28:29], v[28:29]
	v_max_f32_e32 v30, 0, v30
	v_max_f32_e32 v31, 0, v31
	v_pk_mul_f32 v[30:31], v[30:31], v[30:31]
	v_cvt_pk_bf16_f32 v26, v28, v29
	v_cvt_pk_bf16_f32 v27, v30, v31
	global_store_dwordx4 v[46:47], v[24:27], off

.LBB0_169:
	s_or_b64 exec, exec, s[0:1]
	s_waitcnt lgkmcnt(0)
	v_mov_b32_e32 v18, v176
	v_mov_b32_e32 v20, v177
	v_mov_b32_e32 v19, v18
	v_lshlrev_b64 v[16:17], 13, v[40:41]
	v_lshl_add_u64 v[16:17], s[24:25], 0, v[16:17]
	v_lshl_add_u64 v[16:17], v[196:197], 1, v[16:17]
	v_mov_b32_e32 v21, v20
	s_and_saveexec_b64 s[0:1], vcc
	s_cbranch_execz .LBB0_171
	v_pk_fma_f32 v[8:9], v[92:93], v[18:19], v[8:9] neg_lo:[1,0,0] neg_hi:[1,0,0]
	v_pk_fma_f32 v[8:9], v[8:9], v[20:21], v[88:89]
	v_max_f32_e32 v8, 0, v8
	v_max_f32_e32 v9, 0, v9
	v_pk_mul_f32 v[8:9], v[8:9], v[8:9]
	v_pk_fma_f32 v[14:15], v[102:103], v[18:19], v[14:15]
	v_pk_fma_f32 v[10:11], v[94:95], v[18:19], v[10:11]
	v_pk_fma_f32 v[10:11], v[10:11], v[20:21], v[90:91]
	v_max_f32_e32 v10, 0, v10
	v_max_f32_e32 v11, 0, v11
	v_pk_fma_f32 v[12:13], v[100:101], v[18:19], v[12:13] neg_lo:[1,0,0] neg_hi:[1,0,0]
	v_pk_mul_f32 v[10:11], v[10:11], v[10:11]
	v_pk_fma_f32 v[12:13], v[12:13], v[20:21], v[96:97]
	v_cvt_pk_bf16_f32 v8, v8, v9
	v_cvt_pk_bf16_f32 v9, v10, v11
	v_max_f32_e32 v12, 0, v12
	v_max_f32_e32 v13, 0, v13
	v_pk_fma_f32 v[14:15], v[14:15], v[20:21], v[98:99]
	v_pk_mul_f32 v[12:13], v[12:13], v[12:13]
	v_max_f32_e32 v14, 0, v14
	v_max_f32_e32 v15, 0, v15
	v_pk_mul_f32 v[14:15], v[14:15], v[14:15]
	v_cvt_pk_bf16_f32 v10, v12, v13
	v_cvt_pk_bf16_f32 v11, v14, v15
	global_store_dwordx4 v[16:17], v[8:11], off
